# scan derive: LDS writes of r, v and k vectors issued as soon as each is ready (interleaved with VALU) instead of in a burst at the end
# baseline (speedup 1.0000x reference)
.LBB0_979:
	s_waitcnt vmcnt(4)
	v_lshlrev_b32_e32 v30, 16, v50
	v_and_b32_e32 v31, 0xffff0000, v50
	v_lshlrev_b32_e32 v32, 16, v51
	v_and_b32_e32 v33, 0xffff0000, v51
	v_lshlrev_b32_e32 v1, 16, v56
	v_and_b32_e32 v34, 0xffff0000, v56
	v_lshlrev_b32_e32 v46, 16, v57
	v_and_b32_e32 v35, 0xffff0000, v57
	s_waitcnt vmcnt(3)
	v_lshlrev_b32_e32 v36, 16, v52
	v_and_b32_e32 v37, 0xffff0000, v52
	v_lshlrev_b32_e32 v38, 16, v53
	v_and_b32_e32 v39, 0xffff0000, v53
	v_lshlrev_b32_e32 v47, 16, v58
	v_and_b32_e32 v84, 0xffff0000, v58
	v_lshlrev_b32_e32 v85, 16, v59
	v_and_b32_e32 v86, 0xffff0000, v59
	v_sub_f32_e32 v45, v34, v31
	v_sub_f32_e32 v44, v1, v30
	v_sub_f32_e32 v35, v35, v33
	v_sub_f32_e32 v34, v46, v32
	v_pk_fma_f32 v[34:35], v[4:5], v[34:35], v[32:33]
	v_pk_fma_f32 v[32:33], v[2:3], v[44:45], v[30:31]
	ds_write_b128 v155, v[32:35] offset:32768
	v_sub_f32_e32 v31, v84, v37
	v_sub_f32_e32 v30, v47, v36
	v_sub_f32_e32 v45, v86, v39
	v_sub_f32_e32 v44, v85, v38
	s_waitcnt vmcnt(2)
	v_lshlrev_b32_e32 v40, 16, v54
	v_and_b32_e32 v41, 0xffff0000, v54
	v_lshlrev_b32_e32 v42, 16, v55
	v_and_b32_e32 v43, 0xffff0000, v55
	v_lshlrev_b32_e32 v87, 16, v60
	v_and_b32_e32 v88, 0xffff0000, v60
	v_lshlrev_b32_e32 v89, 16, v61
	v_and_b32_e32 v90, 0xffff0000, v61
	v_pk_fma_f32 v[44:45], v[8:9], v[44:45], v[38:39]
	v_pk_fma_f32 v[30:31], v[6:7], v[30:31], v[36:37]
	v_sub_f32_e32 v37, v88, v41
	v_sub_f32_e32 v36, v87, v40
	v_sub_f32_e32 v39, v90, v43
	v_sub_f32_e32 v38, v89, v42
	v_pk_mul_f32 v[84:85], v[14:15], v[30:31]
	v_pk_mul_f32 v[86:87], v[16:17], v[44:45]
	v_pk_fma_f32 v[38:39], v[12:13], v[38:39], v[42:43]
	v_pk_fma_f32 v[36:37], v[10:11], v[36:37], v[40:41]
	ds_write_b128 v155, v[36:39] offset:40960
	v_pk_mul_f32 v[40:41], v[86:87], v[86:87]
	v_pk_mul_f32 v[42:43], v[84:85], v[84:85]
	s_waitcnt vmcnt(1)
	v_lshlrev_b32_e32 v48, 16, v70
	v_pk_mov_b32 v[46:47], v[42:43], v[40:41] op_sel:[1,0]
	v_mov_b32_e32 v43, v41
	v_pk_add_f32 v[40:41], v[46:47], v[42:43]
	v_and_b32_e32 v49, 0xffff0000, v70
	v_lshlrev_b32_e32 v80, 16, v71
	v_and_b32_e32 v81, 0xffff0000, v71
	v_add_f32_e32 v1, v40, v41
	v_pk_add_f32 v[40:41], v[80:81], -1.0 op_sel_hi:[1,0]
	v_pk_add_f32 v[42:43], v[48:49], -1.0 op_sel_hi:[1,0]
	v_add_f32_dpp v1, v1, v1 quad_perm:[1,0,3,2] row_mask:0xf bank_mask:0xf bound_ctrl:1
	v_pk_fma_f32 v[46:47], v[18:19], v[42:43], 1.0 op_sel_hi:[1,1,0]
	v_pk_fma_f32 v[40:41], v[20:21], v[40:41], 1.0 op_sel_hi:[1,1,0]
	v_add_f32_dpp v1, v1, v1 quad_perm:[2,3,0,1] row_mask:0xf bank_mask:0xf bound_ctrl:1
	v_pk_mul_f32 v[42:43], v[44:45], v[40:41]
	v_pk_mul_f32 v[40:41], v[30:31], v[46:47]
	ds_write_b128 v155, v[40:43] offset:24576
	v_add_f32_dpp v1, v1, v1 row_half_mirror row_mask:0xf bank_mask:0xf bound_ctrl:1
	v_pk_mul_f32 v[30:31], v[32:33], v[40:41]
	v_pk_mul_f32 v[44:45], v[34:35], v[42:43]
	v_add_f32_dpp v1, v1, v1 row_ror:8 row_mask:0xf bank_mask:0xf bound_ctrl:1
	v_max_f32_e32 v1, 0x179abe15, v1
	v_pk_mul_f32 v[44:45], v[24:25], v[44:45]
	v_pk_mul_f32 v[30:31], v[22:23], v[30:31]
	v_rsq_f32_e32 v88, v1
	v_add_f32_e32 v1, v30, v31
	v_add_f32_e32 v30, v44, v45
	s_waitcnt vmcnt(0)
	v_exp_f32_e32 v44, v26
	v_exp_f32_e32 v45, v27
	v_exp_f32_e32 v46, v28
	v_exp_f32_e32 v47, v29
	v_add_f32_e32 v1, v1, v30
	ds_write_b128 v155, v[44:47]
	s_nop 0
	v_add_f32_dpp v1, v1, v1 quad_perm:[1,0,3,2] row_mask:0xf bank_mask:0xf bound_ctrl:1
	v_pk_mul_f32 v[46:47], v[86:87], v[88:89] op_sel_hi:[1,0] neg_lo:[0,1] neg_hi:[0,1]
	v_pk_mul_f32 v[44:45], v[84:85], v[88:89] op_sel_hi:[1,0] neg_lo:[0,1] neg_hi:[0,1]
	v_add_f32_dpp v1, v1, v1 quad_perm:[2,3,0,1] row_mask:0xf bank_mask:0xf bound_ctrl:1
	ds_write_b128 v155, v[44:47] offset:8192
	v_pk_mul_f32 v[46:47], v[46:47], v[80:81] neg_lo:[1,0] neg_hi:[1,0]
	v_add_f32_dpp v1, v1, v1 row_half_mirror row_mask:0xf bank_mask:0xf bound_ctrl:1
	v_pk_mul_f32 v[44:45], v[44:45], v[48:49] neg_lo:[1,0] neg_hi:[1,0]
	ds_write_b128 v155, v[44:47] offset:16384
	v_mov_b32_dpp v30, v1 row_ror:8 row_mask:0xf bank_mask:0xf bound_ctrl:1
	s_and_saveexec_b64 s[24:25], s[14:15]
	v_add_f32_e32 v1, v1, v30
	s_bitcmp1_b32 s48, 0
	s_cselect_b32 s100, 0x10100, 0
	v_add_u32_e32 v111, s100, v160
	ds_write_b32 v111, v1 offset:49152
	s_or_b64 exec, exec, s[24:25]
	s_add_i32 s49, s48, 1
	s_cmpk_eq_i32 s48, 0xff
	s_waitcnt lgkmcnt(0)
	s_barrier
	s_cbranch_scc1 .LBB0_985
	v_lshl_add_u32 v26, s49, 5, v154
	v_mad_i64_i32 v[28:29], s[24:25], v26, s59, v[68:69]
	v_add_co_u32_e32 v30, vcc, 0x1000, v28
	v_mov_b32_e32 v1, v0
	s_nop 0
	v_addc_co_u32_e32 v31, vcc, 0, v29, vcc
	global_load_dwordx2 v[50:51], v[28:29], off offset:3072
	global_load_dwordx2 v[52:53], v[30:31], off
	global_load_dwordx2 v[54:55], v[30:31], off offset:1024
	v_cmp_lt_i32_e32 vcc, 0, v26
	v_mov_b64_e32 v[60:61], v[0:1]
	v_mov_b64_e32 v[58:59], v[0:1]
	v_mov_b64_e32 v[56:57], v[0:1]
	s_and_saveexec_b64 s[24:25], vcc
	s_cbranch_execz .LBB0_984
	global_load_dwordx2 v[56:57], v[28:29], off offset:-3616
	global_load_dwordx2 v[58:59], v[28:29], off offset:-2592
	global_load_dwordx2 v[60:61], v[28:29], off offset:-1568

.LBB0_3080:
	s_waitcnt vmcnt(4)
	v_lshlrev_b32_e32 v30, 16, v50
	v_and_b32_e32 v31, 0xffff0000, v50
	v_lshlrev_b32_e32 v32, 16, v51
	v_and_b32_e32 v33, 0xffff0000, v51
	v_lshlrev_b32_e32 v1, 16, v56
	v_and_b32_e32 v34, 0xffff0000, v56
	v_lshlrev_b32_e32 v46, 16, v57
	v_and_b32_e32 v35, 0xffff0000, v57
	s_waitcnt vmcnt(3)
	v_lshlrev_b32_e32 v36, 16, v52
	v_and_b32_e32 v37, 0xffff0000, v52
	v_lshlrev_b32_e32 v38, 16, v53
	v_and_b32_e32 v39, 0xffff0000, v53
	v_lshlrev_b32_e32 v47, 16, v58
	v_and_b32_e32 v84, 0xffff0000, v58
	v_lshlrev_b32_e32 v85, 16, v59
	v_and_b32_e32 v86, 0xffff0000, v59
	v_sub_f32_e32 v45, v34, v31
	v_sub_f32_e32 v44, v1, v30
	v_sub_f32_e32 v35, v35, v33
	v_sub_f32_e32 v34, v46, v32
	v_pk_fma_f32 v[34:35], v[4:5], v[34:35], v[32:33]
	v_pk_fma_f32 v[32:33], v[2:3], v[44:45], v[30:31]
	ds_write_b128 v155, v[32:35] offset:32768
	v_sub_f32_e32 v31, v84, v37
	v_sub_f32_e32 v30, v47, v36
	v_sub_f32_e32 v45, v86, v39
	v_sub_f32_e32 v44, v85, v38
	s_waitcnt vmcnt(2)
	v_lshlrev_b32_e32 v40, 16, v54
	v_and_b32_e32 v41, 0xffff0000, v54
	v_lshlrev_b32_e32 v42, 16, v55
	v_and_b32_e32 v43, 0xffff0000, v55
	v_lshlrev_b32_e32 v87, 16, v60
	v_and_b32_e32 v88, 0xffff0000, v60
	v_lshlrev_b32_e32 v89, 16, v61
	v_and_b32_e32 v90, 0xffff0000, v61
	v_pk_fma_f32 v[44:45], v[8:9], v[44:45], v[38:39]
	v_pk_fma_f32 v[30:31], v[6:7], v[30:31], v[36:37]
	v_sub_f32_e32 v37, v88, v41
	v_sub_f32_e32 v36, v87, v40
	v_sub_f32_e32 v39, v90, v43
	v_sub_f32_e32 v38, v89, v42
	v_pk_mul_f32 v[84:85], v[14:15], v[30:31]
	v_pk_mul_f32 v[86:87], v[16:17], v[44:45]
	v_pk_fma_f32 v[38:39], v[12:13], v[38:39], v[42:43]
	v_pk_fma_f32 v[36:37], v[10:11], v[36:37], v[40:41]
	ds_write_b128 v155, v[36:39] offset:40960
	v_pk_mul_f32 v[40:41], v[86:87], v[86:87]
	v_pk_mul_f32 v[42:43], v[84:85], v[84:85]
	s_waitcnt vmcnt(1)
	v_lshlrev_b32_e32 v48, 16, v70
	v_pk_mov_b32 v[46:47], v[42:43], v[40:41] op_sel:[1,0]
	v_mov_b32_e32 v43, v41
	v_pk_add_f32 v[40:41], v[46:47], v[42:43]
	v_and_b32_e32 v49, 0xffff0000, v70
	v_lshlrev_b32_e32 v80, 16, v71
	v_and_b32_e32 v81, 0xffff0000, v71
	v_add_f32_e32 v1, v40, v41
	v_pk_add_f32 v[40:41], v[80:81], -1.0 op_sel_hi:[1,0]
	v_pk_add_f32 v[42:43], v[48:49], -1.0 op_sel_hi:[1,0]
	v_add_f32_dpp v1, v1, v1 quad_perm:[1,0,3,2] row_mask:0xf bank_mask:0xf bound_ctrl:1
	v_pk_fma_f32 v[46:47], v[18:19], v[42:43], 1.0 op_sel_hi:[1,1,0]
	v_pk_fma_f32 v[40:41], v[20:21], v[40:41], 1.0 op_sel_hi:[1,1,0]
	v_add_f32_dpp v1, v1, v1 quad_perm:[2,3,0,1] row_mask:0xf bank_mask:0xf bound_ctrl:1
	v_pk_mul_f32 v[42:43], v[44:45], v[40:41]
	v_pk_mul_f32 v[40:41], v[30:31], v[46:47]
	ds_write_b128 v155, v[40:43] offset:24576
	v_add_f32_dpp v1, v1, v1 row_half_mirror row_mask:0xf bank_mask:0xf bound_ctrl:1
	v_pk_mul_f32 v[30:31], v[32:33], v[40:41]
	v_pk_mul_f32 v[44:45], v[34:35], v[42:43]
	v_add_f32_dpp v1, v1, v1 row_ror:8 row_mask:0xf bank_mask:0xf bound_ctrl:1
	v_max_f32_e32 v1, 0x179abe15, v1
	v_pk_mul_f32 v[44:45], v[24:25], v[44:45]
	v_pk_mul_f32 v[30:31], v[22:23], v[30:31]
	v_rsq_f32_e32 v88, v1
	v_add_f32_e32 v1, v30, v31
	v_add_f32_e32 v30, v44, v45
	s_waitcnt vmcnt(0)
	v_exp_f32_e32 v44, v26
	v_exp_f32_e32 v45, v27
	v_exp_f32_e32 v46, v28
	v_exp_f32_e32 v47, v29
	v_add_f32_e32 v1, v1, v30
	ds_write_b128 v155, v[44:47]
	s_nop 0
	v_add_f32_dpp v1, v1, v1 quad_perm:[1,0,3,2] row_mask:0xf bank_mask:0xf bound_ctrl:1
	v_pk_mul_f32 v[46:47], v[86:87], v[88:89] op_sel_hi:[1,0] neg_lo:[0,1] neg_hi:[0,1]
	v_pk_mul_f32 v[44:45], v[84:85], v[88:89] op_sel_hi:[1,0] neg_lo:[0,1] neg_hi:[0,1]
	v_add_f32_dpp v1, v1, v1 quad_perm:[2,3,0,1] row_mask:0xf bank_mask:0xf bound_ctrl:1
	ds_write_b128 v155, v[44:47] offset:8192
	v_pk_mul_f32 v[46:47], v[46:47], v[80:81] neg_lo:[1,0] neg_hi:[1,0]
	v_add_f32_dpp v1, v1, v1 row_half_mirror row_mask:0xf bank_mask:0xf bound_ctrl:1
	v_pk_mul_f32 v[44:45], v[44:45], v[48:49] neg_lo:[1,0] neg_hi:[1,0]
	ds_write_b128 v155, v[44:47] offset:16384
	v_mov_b32_dpp v30, v1 row_ror:8 row_mask:0xf bank_mask:0xf bound_ctrl:1
	s_and_saveexec_b64 s[30:31], s[20:21]
	v_add_f32_e32 v1, v1, v30
	s_bitcmp1_b32 s0, 0
	s_cselect_b32 s100, 0x10100, 0
	v_add_u32_e32 v111, s100, v160
	ds_write_b32 v111, v1 offset:49152
	s_or_b64 exec, exec, s[30:31]
	s_add_i32 s1, s0, 1
	s_cmpk_eq_i32 s0, 0xff
	s_waitcnt lgkmcnt(0)
	s_barrier
	s_cbranch_scc1 .LBB0_3086
	v_lshl_add_u32 v26, s1, 5, v154
	v_mad_i64_i32 v[28:29], s[4:5], v26, s72, v[68:69]
	v_add_co_u32_e32 v30, vcc, 0x1000, v28
	v_mov_b32_e32 v1, v0
	s_nop 0
	v_addc_co_u32_e32 v31, vcc, 0, v29, vcc
	global_load_dwordx2 v[50:51], v[28:29], off offset:3072
	global_load_dwordx2 v[52:53], v[30:31], off
	global_load_dwordx2 v[54:55], v[30:31], off offset:1024
	v_cmp_lt_i32_e32 vcc, 0, v26
	v_mov_b64_e32 v[60:61], v[0:1]
	v_mov_b64_e32 v[58:59], v[0:1]
	v_mov_b64_e32 v[56:57], v[0:1]
	s_and_saveexec_b64 s[30:31], vcc
	s_cbranch_execz .LBB0_3085
	global_load_dwordx2 v[56:57], v[28:29], off offset:-3616
	global_load_dwordx2 v[58:59], v[28:29], off offset:-2592
	global_load_dwordx2 v[60:61], v[28:29], off offset:-1568
